# v29 + XCD-local seams ph3->4, ph4->5, ph11->12 (no wbl2/inv/cross-XCD counter; guarded by runtime xcc==bx%8 flag), gr_pass dealt per XCD
# baseline (speedup 1.0000x reference)
; #define LAS __attribute__((address_space(3)))
; __device__ __forceinline__ unsigned xb_add(unsigned* p, unsigned v) { return __hip_atomic_fetch_add(p, v, __ATOMIC_RELAXED, __HIP_MEMORY_SCOPE_AGENT); }
; __device__ __forceinline__ unsigned xb_xcc_id() { return (unsigned)__builtin_amdgcn_s_getreg((3 << 11) | 20) & 0xFu; }
; __device__ __forceinline__ XcdBarrier xcd_barrier_post(unsigned* bar, volatile LAS unsigned* st) {
;     XcdBarrier b; b.bar = bar; b.x = xb_xcc_id(); b.st = st;
;     if (threadIdx.x == 0) (void)xb_add(&bar[XB_XCNT(b.x)], 1u);
;     return b;
; __global__ void __launch_bounds__(NT, 2) fwd_kernel(Params P) {
;     ...
;     const int lo = P.ph_lo, hi = (gridDim.x == 256 && P.ph_hi == 14) ? 13 : P.ph_hi;
;     ...
;     if (threadIdx.x < 4) ((unsigned*)(lds + LDS_MAIN))[threadIdx.x] = 0u;
;     __syncthreads();
;     const XcdBarrier xbar = xcd_barrier_post((unsigned*)(ws + O_BAR), (volatile LAS unsigned*)(ldsl + LDS_MAIN));
_Z10fwd_kernel6Params:
	s_load_dwordx8 s[52:59], s[0:1], 0xb8
	s_add_u32 s8, s0, 0xd0
	v_and_b32_e32 v210, 0x3ff, v0
	s_addc_u32 s9, s1, 0
	v_cmp_gt_u32_e32 vcc, 4, v210
	s_and_saveexec_b64 s[4:5], vcc
	v_lshl_add_u32 v1, v210, 2, 0
	v_add_u32_e32 v1, 0x20000, v1
	v_mov_b32_e32 v2, 0
	ds_write_b32 v1, v2
	s_or_b64 exec, exec, s[4:5]
	s_load_dword s96, s[0:1], 0xd8
	s_waitcnt lgkmcnt(0)
	s_barrier
	s_add_u32 s50, s54, 0x3085c00
	s_getreg_b32 s3, hwreg(HW_REG_XCC_ID, 0, 4)
	s_addc_u32 s51, s55, 0
	s_and_b32 s33, s3, 15
	v_cmp_eq_u32_e64 s[4:5], 0, v210
	s_and_saveexec_b64 s[6:7], s[4:5]
	s_cbranch_execz .LBB0_5
	s_mov_b64 s[10:11], exec
	v_mbcnt_lo_u32_b32 v1, s10, 0
	v_mbcnt_hi_u32_b32 v1, s11, v1
	v_cmp_eq_u32_e32 vcc, 0, v1
	s_and_b64 s[12:13], exec, vcc
	s_mov_b64 exec, s[12:13]
	s_cbranch_execz .LBB0_5
	s_lshl_b32 s3, s33, 8
	s_bcnt1_i32_b64 s10, s[10:11]
	v_mov_b32_e32 v1, s3
	v_mov_b32_e32 v2, s10
	global_atomic_add v1, v2, s[50:51] offset:1024
	s_and_b32 s3, s2, 7
	s_cmp_lg_u32 s3, s33
	s_cselect_b32 s3, 1, 0
	s_cmpk_lg_i32 s58, 0x100
	s_cselect_b32 s10, 1, 0
	s_or_b32 s3, s3, s10
	s_cmp_eq_u32 s3, 0
	s_cbranch_scc1 .Lxmap_ok
	v_mov_b32_e32 v1, 0
	v_mov_b32_e32 v2, 1
	global_atomic_or v1, v2, s[50:51] offset:256
.Lxmap_ok:
.LBB0_5:
	s_or_b64 exec, exec, s[6:7]
	s_cmpk_lt_i32 s56, 0x3e9
	s_cbranch_scc1 .LBB0_17
	v_lshrrev_b32_e32 v1, 20, v0
	v_lshrrev_b32_e32 v0, 10, v0
	v_or_b32_e32 v0, v0, v1
	s_movk_i32 s3, 0x3ff
	v_and_or_b32 v0, v0, s3, v210
	v_cmp_eq_u32_e32 vcc, 0, v0
	s_barrier
	s_and_saveexec_b64 s[6:7], vcc
	s_cbranch_execz .LBB0_16
	buffer_wbl2 sc1
	s_waitcnt vmcnt(0)
	s_load_dwordx2 s[8:9], s[8:9], 0x58
	v_mov_b32_e32 v2, 0
	s_mov_b64 s[10:11], exec
	v_mbcnt_lo_u32_b32 v1, s10, 0
	v_mbcnt_hi_u32_b32 v1, s11, v1
	s_waitcnt lgkmcnt(0)
	global_load_dword v0, v2, s[8:9] offset:40
	v_cmp_eq_u32_e32 vcc, 0, v1
	s_and_saveexec_b64 s[12:13], vcc
	s_cbranch_execz .LBB0_9
	s_bcnt1_i32_b64 s3, s[10:11]
	v_mov_b32_e32 v3, s3
	global_atomic_add v3, v2, v3, s[8:9] offset:32 sc0

; __device__ __forceinline__ unsigned xb_add(unsigned* p, unsigned v) { return __hip_atomic_fetch_add(p, v, __ATOMIC_RELAXED, __HIP_MEMORY_SCOPE_AGENT); }
; __device__ __forceinline__ void xcd_barrier(const XcdBarrier& b) {
;     asm volatile("s_waitcnt vmcnt(0)" ::: "memory");
;     __syncthreads();
;     if (threadIdx.x == 0) {
;         unsigned* bar = b.bar;
;         __builtin_amdgcn_s_waitcnt(0);
;         unsigned nloc = b.st[0], nx = b.st[1];
;         if (nloc == 0u) { xcd_barrier_complete(bar, b.x, nloc, nx); b.st[0] = nloc; b.st[1] = nx; }
;         const unsigned old = xb_add(&bar[XB_XSUB(b.x)], 1u);
;         const unsigned gen = old / nloc;
;         if (old + 1u == (gen + 1u) * nloc) {
.LBB0_1679:
	s_cmp_lt_i32 s57, 5
	s_cbranch_scc1 .LBB0_1733
	s_waitcnt vmcnt(0)
	s_waitcnt vmcnt(0) lgkmcnt(0)
	s_barrier
	s_and_saveexec_b64 s[6:7], s[4:5]
	s_cbranch_execz .LBB0_1732
	v_mov_b32_e32 v0, 0
	global_load_dword v1, v0, s[50:51] offset:256 sc1
	s_lshl_b32 s3, s33, 8
	s_add_u32 s8, s50, s3
	s_addc_u32 s9, s51, 0
	v_mov_b32_e32 v3, 0x2000
	global_load_dword v4, v3, s[8:9] offset:1024 sc1
	v_mov_b32_e32 v2, 0x20000
	ds_read_b32 v2, v2
	s_waitcnt vmcnt(0) lgkmcnt(0)
	v_readfirstlane_b32 s10, v1
	v_readfirstlane_b32 s11, v4
	v_readfirstlane_b32 s12, v2
	s_nop 1
	s_cmp_lg_u32 s10, 0
	s_cbranch_scc1 .Lseam34_full
	s_cmp_eq_u32 s12, 0
	s_cbranch_scc1 .Lseam34_full
	v_mov_b32_e32 v3, 0x1000
	v_mov_b32_e32 v5, 1
	global_atomic_add v3, v3, v5, s[8:9] offset:1024 sc0
	s_waitcnt vmcnt(0)
	v_readfirstlane_b32 s13, v3
	s_add_i32 s14, s11, 1
	s_mul_i32 s14, s14, s12
	s_add_i32 s13, s13, 1
	v_mov_b32_e32 v3, 0x2000
	s_cmp_eq_u32 s13, s14
	s_cbranch_scc1 .Lseam34_lead
.Lseam34_spin:
	s_sleep 1
	global_load_dword v4, v3, s[8:9] offset:1024 sc1
	s_waitcnt vmcnt(0)
	v_readfirstlane_b32 s15, v4
	s_nop 1
	s_cmp_eq_u32 s15, s11
	s_cbranch_scc1 .Lseam34_spin
	s_branch .Lseam34_done
.Lseam34_lead:
	global_atomic_add v3, v5, s[8:9] offset:1024
	s_waitcnt vmcnt(0)
.Lseam34_done:
	buffer_inv sc0
	s_waitcnt vmcnt(0)
	s_branch .LBB0_1732
.Lseam34_full:
	s_add_i32 s3, 0, 0x20000
	v_mov_b32_e32 v0, s3
	s_waitcnt vmcnt(0) expcnt(0) lgkmcnt(0)
	ds_read_b32 v2, v0
	s_add_i32 s3, 0, 0x20004
	v_mov_b32_e32 v0, s3
	ds_read_b32 v0, v0
	s_waitcnt lgkmcnt(1)
	v_cmp_ne_u32_e32 vcc, 0, v2
	s_cbranch_vccnz .LBB0_1696
	s_add_u32 s8, s54, 0x3085e00
	s_addc_u32 s9, s55, 0
	s_add_u32 s10, s54, 0x3086000
	s_addc_u32 s11, s55, 0
	s_add_u32 s12, s54, 0x3086100
	s_addc_u32 s13, s55, 0
	s_add_u32 s14, s54, 0x3086200
	s_addc_u32 s15, s55, 0
	s_add_u32 s16, s54, 0x3086300
	s_addc_u32 s17, s55, 0
	s_add_u32 s18, s54, 0x3086400
	s_addc_u32 s19, s55, 0
	s_add_u32 s20, s54, 0x3086500
	s_addc_u32 s21, s55, 0
	s_add_u32 s22, s54, 0x3086600
	s_addc_u32 s23, s55, 0
	s_add_u32 s24, s54, 0x3086700
	s_addc_u32 s25, s55, 0
	s_add_u32 s26, s54, 0x3086800
	s_addc_u32 s27, s55, 0
	s_add_u32 s28, s54, 0x3086900
	s_addc_u32 s29, s55, 0
	s_add_u32 s30, s54, 0x3086a00
	s_addc_u32 s31, s55, 0
	s_add_u32 s34, s54, 0x3086b00
	s_addc_u32 s35, s55, 0
	s_add_u32 s36, s54, 0x3086c00
	s_addc_u32 s37, s55, 0
	s_add_u32 s38, s54, 0x3086d00
	s_addc_u32 s39, s55, 0
	s_add_u32 s40, s54, 0x3086e00
	s_addc_u32 s41, s55, 0
	s_mul_i32 s3, s59, s96
	s_add_u32 s42, s54, 0x3086f00
	s_mul_i32 s3, s3, s58
	s_addc_u32 s43, s55, 0
	s_mov_b32 s60, 1
	v_mov_b32_e32 v16, 0
	s_branch .LBB0_1684

; __device__ __forceinline__ unsigned xb_add(unsigned* p, unsigned v) { return __hip_atomic_fetch_add(p, v, __ATOMIC_RELAXED, __HIP_MEMORY_SCOPE_AGENT); }
; __device__ __forceinline__ void xcd_barrier(const XcdBarrier& b) {
;     asm volatile("s_waitcnt vmcnt(0)" ::: "memory");
;     __syncthreads();
;     if (threadIdx.x == 0) {
;         unsigned* bar = b.bar;
;         __builtin_amdgcn_s_waitcnt(0);
;         unsigned nloc = b.st[0], nx = b.st[1];
;         if (nloc == 0u) { xcd_barrier_complete(bar, b.x, nloc, nx); b.st[0] = nloc; b.st[1] = nx; }
;         const unsigned old = xb_add(&bar[XB_XSUB(b.x)], 1u);
;         const unsigned gen = old / nloc;
;         if (old + 1u == (gen + 1u) * nloc) {
.LBB0_1779:
	s_cmp_lt_i32 s57, 6
	s_cbranch_scc1 .LBB0_1833
	s_waitcnt vmcnt(0)
	s_waitcnt vmcnt(0) lgkmcnt(0)
	s_barrier
	s_and_saveexec_b64 s[6:7], s[4:5]
	s_cbranch_execz .LBB0_1832
	v_mov_b32_e32 v0, 0
	global_load_dword v1, v0, s[50:51] offset:256 sc1
	s_lshl_b32 s3, s33, 8
	s_add_u32 s8, s50, s3
	s_addc_u32 s9, s51, 0
	v_mov_b32_e32 v3, 0x2000
	global_load_dword v4, v3, s[8:9] offset:1024 sc1
	v_mov_b32_e32 v2, 0x20000
	ds_read_b32 v2, v2
	s_waitcnt vmcnt(0) lgkmcnt(0)
	v_readfirstlane_b32 s10, v1
	v_readfirstlane_b32 s11, v4
	v_readfirstlane_b32 s12, v2
	s_nop 1
	s_cmp_lg_u32 s10, 0
	s_cbranch_scc1 .Lseam45_full
	s_cmp_eq_u32 s12, 0
	s_cbranch_scc1 .Lseam45_full
	v_mov_b32_e32 v3, 0x1000
	v_mov_b32_e32 v5, 1
	global_atomic_add v3, v3, v5, s[8:9] offset:1024 sc0
	s_waitcnt vmcnt(0)
	v_readfirstlane_b32 s13, v3
	s_add_i32 s14, s11, 1
	s_mul_i32 s14, s14, s12
	s_add_i32 s13, s13, 1
	v_mov_b32_e32 v3, 0x2000
	s_cmp_eq_u32 s13, s14
	s_cbranch_scc1 .Lseam45_lead

; __device__ __forceinline__ void gr_pass(const bf16_t* hb, const bf16_t* WgrT, const float* ssq_in, float* gr) {
;     const int lane = threadIdx.x & 63, wid = threadIdx.x >> 6, fr = lane & 15, fq = lane >> 4;
;     for (int gidx = blockIdx.x * 8 + wid; gidx < M / 16; gidx += gridDim.x * 8) {
;         const int r0 = gidx * 16; f32x4 acc = (f32x4){0.f, 0.f, 0.f, 0.f};
;         const bf16_t* ap = hb + (size_t)(r0 + fr) * D + 8 * fq; const bf16_t* bp = WgrT + (size_t)fr * D + 8 * fq;
.LBB0_1833:
	s_cmp_lt_i32 s56, 6
	s_cselect_b64 s[6:7], -1, 0
	s_cmp_gt_i32 s57, 5
	s_cselect_b64 s[8:9], -1, 0
	s_and_b64 s[6:7], s[6:7], s[8:9]
	s_andn2_b64 vcc, exec, s[6:7]
	s_cbranch_vccnz .LBB0_1958
	v_lshrrev_b32_e32 v0, 6, v210
	s_nop 0
	v_readfirstlane_b32 s12, v0
	s_lshr_b32 s6, s2, 3
	s_and_b32 s7, s2, 7
	s_lshl_b32 s10, s7, 7
	s_lshl_b32 s11, s6, 3
	s_add_i32 s10, s10, s11
	s_add_i32 s10, s10, s12
	s_lshl_b32 s11, s7, 1
	s_add_i32 s11, s11, s12
	s_addk_i32 s11, 0x400
	s_cmp_lt_u32 s12, 2
	s_cselect_b32 s11, s11, 0x7fff
	s_cmp_eq_u32 s6, 16
	s_cselect_b32 s11, s11, 0x7fff
	s_cmp_lt_u32 s6, 16
	s_cselect_b32 s10, s10, s11
	s_lshl_b32 s11, s2, 3
	s_add_i32 s11, s11, s12
	s_cmpk_eq_i32 s58, 0x100
	s_cselect_b32 s10, s10, s11
	v_mov_b32_e32 v16, s10
	s_add_u32 s34, s54, 0x2fac800
	s_movk_i32 s3, 0x410
	s_addc_u32 s35, s55, 0
	v_cmp_gt_i32_e32 vcc, s3, v16
	s_and_saveexec_b64 s[8:9], vcc
	s_cbranch_execz .LBB0_1839
	s_waitcnt lgkmcnt(0)
	v_and_b32_e32 v1, 15, v210
	v_bfe_u32 v8, v210, 4, 2
	v_lshlrev_b32_e32 v4, 2, v1
	v_mov_b32_e32 v5, 0
	v_lshl_add_u64 v[2:3], s[54:55], 0, v[4:5]
	v_lshlrev_b32_e32 v4, 4, v8
	v_lshlrev_b32_e32 v0, 4, v0
	v_lshlrev_b32_e32 v17, 2, v8
	s_mov_b64 s[6:7], 0x2e88000
	v_lshl_add_u64 v[8:9], s[54:55], 0, v[4:5]
	v_lshlrev_b32_e32 v0, 4, v16
	v_lshl_or_b32 v4, v1, 11, v4
	v_lshl_add_u64 v[6:7], v[2:3], 0, s[6:7]
	s_lshl_b32 s3, s58, 3
	v_or_b32_e32 v10, v0, v1
	s_lshl_b32 s12, s58, 7
	s_waitcnt vmcnt(0)
	v_lshl_add_u64 v[12:13], s[54:55], 0, v[4:5]
	s_mov_b64 s[10:11], 0
	v_mov_b32_e32 v4, 0x358637bd
	s_mov_b32 s13, 0x800000
	s_movk_i32 s14, 0x40f

; __device__ __forceinline__ unsigned xb_add(unsigned* p, unsigned v) { return __hip_atomic_fetch_add(p, v, __ATOMIC_RELAXED, __HIP_MEMORY_SCOPE_AGENT); }
; __device__ __forceinline__ void xcd_barrier(const XcdBarrier& b) {
;     asm volatile("s_waitcnt vmcnt(0)" ::: "memory");
;     __syncthreads();
;     if (threadIdx.x == 0) {
;         unsigned* bar = b.bar;
;         __builtin_amdgcn_s_waitcnt(0);
;         unsigned nloc = b.st[0], nx = b.st[1];
;         if (nloc == 0u) { xcd_barrier_complete(bar, b.x, nloc, nx); b.st[0] = nloc; b.st[1] = nx; }
;         const unsigned old = xb_add(&bar[XB_XSUB(b.x)], 1u);
;         const unsigned gen = old / nloc;
;         if (old + 1u == (gen + 1u) * nloc) {
.LBB0_2546:
	s_cmp_lt_i32 s57, 13
	s_cbranch_scc1 .LBB0_2600
	s_waitcnt vmcnt(0)
	s_waitcnt lgkmcnt(0)
	s_barrier
	s_and_saveexec_b64 s[6:7], s[4:5]
	s_cbranch_execz .LBB0_2599
	v_mov_b32_e32 v0, 0
	global_load_dword v1, v0, s[50:51] offset:256 sc1
	s_lshl_b32 s3, s33, 8
	s_add_u32 s8, s50, s3
	s_addc_u32 s9, s51, 0
	v_mov_b32_e32 v3, 0x2000
	global_load_dword v4, v3, s[8:9] offset:1024 sc1
	v_mov_b32_e32 v2, 0x20000
	ds_read_b32 v2, v2
	s_waitcnt vmcnt(0) lgkmcnt(0)
	v_readfirstlane_b32 s10, v1
	v_readfirstlane_b32 s11, v4
	v_readfirstlane_b32 s12, v2
	s_nop 1
	s_cmp_lg_u32 s10, 0
	s_cbranch_scc1 .Lseam1112_full
	s_cmp_eq_u32 s12, 0
	s_cbranch_scc1 .Lseam1112_full
	v_mov_b32_e32 v3, 0x1000
	v_mov_b32_e32 v5, 1
	global_atomic_add v3, v3, v5, s[8:9] offset:1024 sc0
	s_waitcnt vmcnt(0)
	v_readfirstlane_b32 s13, v3
	s_add_i32 s14, s11, 1
	s_mul_i32 s14, s14, s12
	s_add_i32 s13, s13, 1
	v_mov_b32_e32 v3, 0x2000
	s_cmp_eq_u32 s13, s14
	s_cbranch_scc1 .Lseam1112_lead
